# phase 0: LP/BB table and zeroing loops run first (before adaLN / transposes) so they no longer sit at the end of the critical adaLN waves; input pointers reloaded afterwards
# speedup vs baseline: 1.0093x; 1.0007x over previous
; __device__ __forceinline__ void phase0(const Params& P, unsigned char* smem) {
;     ...
;     const int gtid = blockIdx.x * NTHR + threadIdx.x, gsz = gridDim.x * NTHR;
;     for (int e = gtid; e < NT + 2 * NL; e += gsz) ((float*)(P.ws + OFF_SS))[e] = 0.f;
.LBB0_10:
	s_mov_b64 s[92:93], s[0:1]
	s_load_dwordx16 s[36:51], s[0:1], 0x0
	s_load_dwordx16 s[4:19], s[0:1], 0x40
	s_cmp_lt_i32 s70, 1
	s_waitcnt lgkmcnt(0)
	s_barrier
	v_writelane_b32 v251, s4, 5
	s_nop 1
	v_writelane_b32 v251, s5, 6
	v_writelane_b32 v251, s6, 7
	v_writelane_b32 v251, s7, 8
	v_writelane_b32 v251, s8, 9
	v_writelane_b32 v251, s9, 10
	v_writelane_b32 v251, s10, 11
	v_writelane_b32 v251, s11, 12
	v_writelane_b32 v251, s12, 13
	v_writelane_b32 v251, s13, 14
	v_writelane_b32 v251, s14, 15
	v_writelane_b32 v251, s15, 16
	v_writelane_b32 v251, s16, 17
	v_writelane_b32 v251, s17, 18
	v_writelane_b32 v251, s18, 19
	v_writelane_b32 v251, s19, 20
	s_load_dwordx16 s[4:19], s[0:1], 0x80
	s_waitcnt lgkmcnt(0)
	v_writelane_b32 v251, s4, 21
	s_nop 1
	v_writelane_b32 v251, s5, 22
	v_writelane_b32 v251, s6, 23
	v_writelane_b32 v251, s7, 24
	v_writelane_b32 v251, s8, 25
	v_writelane_b32 v251, s9, 26
	v_writelane_b32 v251, s10, 27
	v_writelane_b32 v251, s11, 28
	v_writelane_b32 v251, s12, 29
	v_writelane_b32 v251, s13, 30
	v_writelane_b32 v251, s14, 31
	v_writelane_b32 v251, s15, 32
	v_writelane_b32 v251, s16, 33
	v_writelane_b32 v251, s17, 34
	v_writelane_b32 v251, s18, 35
	v_writelane_b32 v251, s19, 36
	s_load_dwordx16 s[4:19], s[0:1], 0xc0
	s_cselect_b64 s[0:1], -1, 0
	s_cmp_gt_i32 s71, 0
	s_cselect_b64 s[2:3], -1, 0
	s_and_b64 s[0:1], s[0:1], s[2:3]
	s_waitcnt lgkmcnt(0)
	v_writelane_b32 v251, s4, 37
	s_andn2_b64 vcc, exec, s[0:1]
	s_mov_b32 s0, 0
	v_writelane_b32 v251, s5, 38
	v_writelane_b32 v251, s6, 39
	v_writelane_b32 v251, s7, 40
	v_writelane_b32 v251, s8, 41
	v_writelane_b32 v251, s9, 42
	v_writelane_b32 v251, s10, 43
	v_writelane_b32 v251, s11, 44
	v_writelane_b32 v251, s12, 45
	v_writelane_b32 v251, s13, 46
	v_writelane_b32 v251, s14, 47
	v_writelane_b32 v251, s15, 48
	v_writelane_b32 v251, s16, 49
	v_writelane_b32 v251, s17, 50
	v_writelane_b32 v251, s18, 51
	v_writelane_b32 v251, s19, 52
	v_writelane_b32 v251, s0, 53
	s_cbranch_vccnz .LBB0_131
	v_readlane_b32 s0, v251, 1
	v_readlane_b32 s1, v251, 2
	s_nop 3
	s_load_dword s2, s[0:1], 0x10
	s_waitcnt lgkmcnt(0)
	s_lshr_b32 s0, s2, 16
	s_and_b32 s0, 0xffff, s0
	s_cmp_lg_u32 s0, 0
	s_cselect_b64 s[0:1], -1, 0
	s_cmp_lg_u64 s[0:1], 0
	s_addc_u32 s30, s90, 0
	v_lshl_add_u32 v2, s33, 9, v168
	s_mov_b32 s0, 0x18400
	s_lshl_b32 s52, s30, 9
	v_cmp_gt_i32_e32 vcc, s0, v2
	s_and_saveexec_b64 s[2:3], vcc
	s_cbranch_execz .LBB0_102
	v_cvt_f32_u32_e32 v1, s52
	v_add_u32_e32 v3, s52, v2
	v_mov_b32_e32 v4, s52
	v_cmp_gt_i32_e32 vcc, s0, v3
	v_rcp_iflag_f32_e32 v1, v1
	s_sub_i32 s4, 0, s52
	v_max_i32_e32 v5, 0x18400, v3
	v_addc_co_u32_e64 v4, s[0:1], v2, v4, vcc
	v_mul_f32_e32 v1, 0x4f7ffffe, v1
	v_cvt_u32_f32_e32 v1, v1
	v_sub_u32_e32 v4, v5, v4
	v_mul_lo_u32 v5, s4, v1
	v_mul_hi_u32 v5, v1, v5
	v_add_u32_e32 v1, v1, v5
	v_mul_hi_u32 v1, v4, v1
	v_mul_lo_u32 v5, v1, s52
	v_sub_u32_e32 v4, v4, v5
	v_add_u32_e32 v6, 1, v1
	v_cmp_le_u32_e64 s[0:1], s52, v4
	v_subrev_u32_e32 v5, s52, v4
	s_mov_b64 s[4:5], -1
	v_cndmask_b32_e64 v1, v1, v6, s[0:1]
	v_cndmask_b32_e64 v4, v4, v5, s[0:1]
	v_add_u32_e32 v5, 1, v1
	v_cmp_le_u32_e64 s[0:1], s52, v4
	v_mov_b32_e32 v4, v2
	s_nop 0
	v_cndmask_b32_e64 v1, v1, v5, s[0:1]
	v_addc_co_u32_e32 v1, vcc, 1, v1, vcc
	v_cmp_lt_u32_e32 vcc, 1, v1
	s_and_saveexec_b64 s[0:1], vcc
	s_cbranch_execz .LBB0_99
	s_add_u32 s4, s68, 0x1ef41000
	s_addc_u32 s5, s69, 0
	v_and_b32_e32 v6, -2, v1
	s_lshl_b32 s7, s30, 10
	s_mov_b32 s20, s7
	s_mov_b64 s[10:11], 0
	v_mov_b32_e32 v7, 0
	v_mov_b32_e32 v8, v6
	v_mov_b64_e32 v[4:5], v[2:3]

; __device__ __forceinline__ float siluf_(float x) { return x * sigm(x); }
; __device__ __forceinline__ void ada_item(const Params& P, int item, float* sm) {
;     float* sv = sm; float* red = sm + 5 * 1024;
;     const int tid = threadIdx.x & 255;
;     for (int e = tid; e < 5 * 1024; e += 256) { const int r = e >> 10, k = e & 1023; const float c = r < 4 ? P.in[1][r * 1024 + k] : P.in[3][k]; sv[e] = siluf_(c); }
;     __syncthreads();
.Ltab_end:
	s_or_b64 exec, exec, s[54:55]
	s_load_dwordx16 s[36:51], s[92:93], 0x0
	s_waitcnt lgkmcnt(0)
	s_nop 0
	s_nop 0
	s_nop 0
	s_nop 0
	s_nop 0
	s_nop 0
	s_nop 0
	s_nop 0
	s_nop 0
	s_nop 0
	s_nop 0
	s_nop 0
	v_lshlrev_b32_e32 v1, 2, v168
	v_add_u32_e32 v2, 0x1000, v1
	v_add_u32_e32 v3, 0x2000, v1
	v_add_u32_e32 v4, 0x3000, v1
	global_load_dword v10, v1, s[38:39]
	global_load_dword v11, v1, s[38:39] offset:2048
	global_load_dword v12, v2, s[38:39]
	global_load_dword v13, v2, s[38:39] offset:2048
	global_load_dword v14, v3, s[38:39]
	global_load_dword v15, v3, s[38:39] offset:2048
	global_load_dword v16, v4, s[38:39]
	global_load_dword v17, v4, s[38:39] offset:2048
	global_load_dword v18, v1, s[42:43]
	global_load_dword v19, v1, s[42:43] offset:2048
	v_and_b32_e32 v6, 7, v168
	v_lshrrev_b32_e32 v7, 3, v168
	v_mul_u32_u24_e32 v6, 0x210, v6
	v_lshl_add_u32 v5, v7, 2, v6
	v_add_u32_e32 v5, 0x13810, v5
	s_waitcnt vmcnt(0)
	v_mul_f32_e32 v20, 0xbfb8aa3b, v10
	v_mul_f32_e32 v21, 0xbfb8aa3b, v11
	v_mul_f32_e32 v22, 0xbfb8aa3b, v12
	v_mul_f32_e32 v23, 0xbfb8aa3b, v13
	v_mul_f32_e32 v24, 0xbfb8aa3b, v14
	v_mul_f32_e32 v25, 0xbfb8aa3b, v15
	v_mul_f32_e32 v26, 0xbfb8aa3b, v16
	v_mul_f32_e32 v27, 0xbfb8aa3b, v17
	v_mul_f32_e32 v28, 0xbfb8aa3b, v18
	v_mul_f32_e32 v29, 0xbfb8aa3b, v19
	v_exp_f32_e32 v20, v20
	v_exp_f32_e32 v21, v21
	v_exp_f32_e32 v22, v22
	v_exp_f32_e32 v23, v23
	v_exp_f32_e32 v24, v24
	v_exp_f32_e32 v25, v25
	v_exp_f32_e32 v26, v26
	v_exp_f32_e32 v27, v27
	v_exp_f32_e32 v28, v28
	v_exp_f32_e32 v29, v29
	v_add_f32_e32 v20, 1.0, v20
	v_add_f32_e32 v21, 1.0, v21
	v_add_f32_e32 v22, 1.0, v22
	v_add_f32_e32 v23, 1.0, v23
	v_add_f32_e32 v24, 1.0, v24
	v_add_f32_e32 v25, 1.0, v25
	v_add_f32_e32 v26, 1.0, v26
	v_add_f32_e32 v27, 1.0, v27
	v_add_f32_e32 v28, 1.0, v28
	v_add_f32_e32 v29, 1.0, v29
	v_rcp_f32_e32 v20, v20
	v_rcp_f32_e32 v21, v21
	v_rcp_f32_e32 v22, v22
	v_rcp_f32_e32 v23, v23
	v_rcp_f32_e32 v24, v24
	v_rcp_f32_e32 v25, v25
	v_rcp_f32_e32 v26, v26
	v_rcp_f32_e32 v27, v27
	v_rcp_f32_e32 v28, v28
	v_rcp_f32_e32 v29, v29
	v_mul_f32_e32 v10, v10, v20
	v_mul_f32_e32 v11, v11, v21
	v_mul_f32_e32 v12, v12, v22
	v_mul_f32_e32 v13, v13, v23
	v_mul_f32_e32 v14, v14, v24
	v_mul_f32_e32 v15, v15, v25
	v_mul_f32_e32 v16, v16, v26
	v_mul_f32_e32 v17, v17, v27
	v_mul_f32_e32 v18, v18, v28
	v_mul_f32_e32 v19, v19, v29
	ds_write_b32 v5, v10
	ds_write_b32 v5, v11 offset:256
	ds_write_b32 v5, v12 offset:4224
	ds_write_b32 v5, v13 offset:4480
	ds_write_b32 v5, v14 offset:8448
	ds_write_b32 v5, v15 offset:8704
	ds_write_b32 v5, v16 offset:12672
	ds_write_b32 v5, v17 offset:12928
	ds_write_b32 v5, v18 offset:16896
	ds_write_b32 v5, v19 offset:17152
	s_waitcnt lgkmcnt(0)
	s_barrier
	v_lshrrev_b32_e32 v6, 6, v168
	s_nop 1
	v_readfirstlane_b32 s0, v6
	s_nop 3
	s_mov_b32 s1, s33
	s_cmp_eq_u32 s0, 0
	s_cbranch_scc1 .Lada_go
	s_cmp_eq_u32 s0, 1
	s_cbranch_scc0 .LBB0_20
	s_cmp_lt_u32 s33, 32
	s_cbranch_scc0 .LBB0_20
	s_add_u32 s1, s33, 0x100

; __device__ __forceinline__ float2 cmul(float2 a, float2 b) { return make_float2(a.x * b.x - a.y * b.y, a.x * b.y + a.y * b.x); }
; __device__ __forceinline__ void phase0(const Params& P, unsigned char* smem) {
;     ...
;     const int gtid = blockIdx.x * NTHR + threadIdx.x, gsz = gridDim.x * NTHR;
;     for (int e = gtid; e < NT + 2 * NL; e += gsz) ((float*)(P.ws + OFF_SS))[e] = 0.f;
;     float2* LP = (float2*)(P.ws + OFF_LP); float2* BB = (float2*)(P.ws + OFF_BB);
;     for (int e = gtid; e < 2 * 32 * 33 * 64; e += gsz) {
;         const int p = e & 63, tau = (e >> 6) % 33, dg = e / (33 * 64);
;         const float lre = fminf(P.in[12][dg * 64 + p], -1e-4f), lim = P.in[13][dg * 64 + p], dt = expf(P.in[14][dg]);
;         const float mag = expf(lre * dt * (float)tau), ang = (lim * dt) * (float)tau;
;         float sn, cs; sincosf(ang, &sn, &cs);
;         LP[e] = make_float2(mag * cs, mag * sn);
;     }
;     for (int e = gtid; e < 2 * 32 * 64 * 16; e += gsz) {
;         const int dgp = e >> 4;
;         const int dg = dgp >> 6;
;         const float lre = fminf(P.in[12][dgp], -1e-4f), lim = P.in[13][dgp], dt = expf(P.in[14][dg]);
;         const float mag = expf(lre * dt), ang = lim * dt;
;         float sn, cs; sincosf(ang, &sn, &cs);
;         const float ar = mag * cs - 1.f, ai = mag * sn;
;         const float den = lre * lre + lim * lim;
;         const float qr = (ar * lre + ai * lim) / den, qi = (ai * lre - ar * lim) / den;
;         BB[e] = cmul(make_float2(qr, qi), make_float2(P.in[15][e], P.in[16][e]));
;     }
.Ltr_pad:
.LBB0_94:
.LBB0_116:
	s_or_b64 exec, exec, s[54:55]
	s_cmp_lt_i32 s71, 2
	s_mov_b32 s0, 0
	v_writelane_b32 v251, s0, 53
	s_cbranch_scc1 .LBB0_131
	v_lshrrev_b32_e32 v1, 20, v0
	v_lshrrev_b32_e32 v0, 10, v0
	v_or_b32_e32 v0, v0, v1
	s_movk_i32 s0, 0x3ff
	v_and_or_b32 v0, v0, s0, v168
	v_cmp_eq_u32_e32 vcc, 0, v0
	s_barrier
	s_and_saveexec_b64 s[0:1], vcc
	s_cbranch_execz .LBB0_127
	v_readlane_b32 s2, v251, 1
	v_readlane_b32 s3, v251, 2
	buffer_wbl2 sc1
	s_waitcnt vmcnt(0)
	s_load_dwordx2 s[2:3], s[2:3], 0x58
	v_mov_b32_e32 v2, 0
	s_mov_b64 s[4:5], exec
	v_mbcnt_lo_u32_b32 v1, s4, 0
	v_mbcnt_hi_u32_b32 v1, s5, v1
	s_waitcnt lgkmcnt(0)
	global_load_dword v0, v2, s[2:3] offset:40
	v_cmp_eq_u32_e32 vcc, 0, v1
	s_and_saveexec_b64 s[6:7], vcc
	s_cbranch_execz .LBB0_120
	s_bcnt1_i32_b64 s4, s[4:5]
	v_mov_b32_e32 v3, s4
	global_atomic_add v3, v2, v3, s[2:3] offset:32 sc0
